# attention ticket queues: the four smallest items of each batch are handed out first so the big-first greedy ends without a tail of tiny third items
# speedup vs baseline: 1.0684x; 1.0040x over previous
.LBB0_474:
	s_andn2_b64 vcc, exec, s[8:9]
	s_cbranch_vccnz .LBB0_477
	s_barrier
	v_mov_b32_e32 v0, 0xf000
	ds_read_b32 v0, v0
	s_waitcnt lgkmcnt(0)
	v_readfirstlane_b32 s14, v0
	s_bfe_u32 s11, s83, 0x10001
	s_cmpk_lt_u32 s14, 0x104
	s_cselect_b64 s[6:7], -1, 0
	s_cmp_lt_u32 s14, 4
	s_cbranch_scc0 .Lq_nottiny
	s_lshl_b32 s11, s11, 8
	s_or_b32 s14, s14, s11
	s_branch .Lq_done
.Lq_nottiny:
	s_add_i32 s14, s14, -4
	s_cmpk_lt_u32 s14, 0xde
	s_cbranch_scc1 .Lq_prompt
	s_cmpk_lt_u32 s14, 0xe2
	s_cbranch_scc0 .Lq_late
	s_lshl_b32 s10, s11, 2
	s_add_i32 s14, s14, s10
	s_addk_i32 s14, 0x122
	s_branch .Lq_done
